# diff-attention: hand-scheduled unmasked tile body (batched LDS reads, counted lgkmcnt, VALU row sums replace ones-MFMA)
# speedup vs baseline: 1.0257x; 1.0257x over previous
; DI int ltid() { int t = threadIdx.x; asm volatile("" : "+v"(t)); return t; }
; template <int DK, int DV, int NM, bool CAUSAL> ...
;     ...
;   const int tid = ltid(), lane = tid & 63, wave = tid >> 6, h = lane >> 5, l31 = lane & 31;
;   const int wq = (NM == 2) ? (wave & 3) : wave;
;   const int mymap = (NM == 2) ? (wave >> 2) : 0;
;   const int q0w = q0 + wq * 32;
;   bf16x8 qf[NKC16];
;   f32x16 o[NDVB];
; #pragma unroll
;   for (int d = 0; d < NDVB; ++d)
; #pragma unroll
;     for (int i = 0; i < 16; ++i) o[d][i] = 0.f;
;   f32x16 lacc;
; #pragma unroll
;   for (int i = 0; i < 16; ++i) lacc[i] = 0.f;
;   u4 onesu; onesu.x = onesu.y = onesu.z = onesu.w = 0x3F803F80u;
;   const bf16x8 ones = __builtin_bit_cast(bf16x8, onesu);
;   const int wu = __builtin_amdgcn_readfirstlane(wave);
;   const int krow = lane >> 4, kslot = lane & 15;
;   const int vrow = lane >> 3, vslot = lane & 7;
;   auto issue = [&](int kt) {
;     char* st = smem + (kt & 3) * STAGE;
; #pragma unroll
;     for (int i = 0; i < 2; ++i) {
;       const int r = (wu * 2 + i) * 4 + krow;
;       const int c = kslot ^ (r & 15);
;       if (KCHV == 16 || c < KCHV)
;         __builtin_amdgcn_global_load_lds((const unsigned*)(Kg + (size_t)(kt * 64 + r) * ldk + c * 8), (unsigned*)(st + (wu * 2 + i) * 1024), 16, 0, 0);
;     }
; #pragma unroll
;     for (int i = 0; i < NVI; ++i) {
;       const int d = (wu * NVI + i) * 8 + vrow;
;       const int c = vslot ^ ((d >> 1) & 7);
;       __builtin_amdgcn_global_load_lds((const unsigned*)(Vt + (size_t)d * ldv + kt * 64 + c * 8), (unsigned*)(st + KBYTES + (wu * NVI + i) * 1024), 16, 0, 0);
;     }
;   };
;   asm volatile("s_waitcnt vmcnt(0)" ::: "memory");
;   __syncthreads();
;   if (0 < nkt) issue(0);
;   if (1 < nkt) issue(1);
;   if (2 < nkt) issue(2);
;   {
;     const bf16_t* qp = Q + (size_t)(wq * 32 + l31) * ldq + mymap * DK + h * 8;
; #pragma unroll
;     for (int kc = 0; kc < NKC16; ++kc) qf[kc] = *(const bf16x8*)(qp + kc * 16);
; #pragma unroll
;     for (int kc = 0; kc < NKC16; ++kc) asm volatile("" : "+v"(qf[kc]));
;   }
.LBB0_90:
	s_xor_b64 s[8:9], s[4:5], -1
	s_or_b32 s4, s16, s30
	s_ashr_i32 s5, s4, 31
	v_and_b32_e32 v162, 3, v159
	s_lshl_b64 s[4:5], s[4:5], 11
	v_lshlrev_b32_e32 v23, 5, v162
	v_and_b32_e32 v24, 31, v158
	s_add_u32 s4, s31, s4
	v_or_b32_e32 v2, v23, v24
	s_addc_u32 s5, s34, s5
	v_ashrrev_i32_e32 v21, 8, v158
	v_lshlrev_b32_e32 v2, 11, v2
	v_mov_b32_e32 v3, v1
	v_and_b32_e32 v161, 63, v158
	v_lshl_add_u64 v[144:145], s[4:5], 0, v[2:3]
	v_lshlrev_b32_e32 v2, 6, v21
	v_lshrrev_b32_e32 v22, 5, v161
	v_ashrrev_i32_e32 v3, 31, v2
	v_lshl_add_u64 v[2:3], v[2:3], 1, v[144:145]
	v_lshlrev_b32_e32 v4, 4, v22
	v_mov_b32_e32 v5, v1
	v_lshl_add_u64 v[2:3], v[2:3], 0, v[4:5]
	flat_load_dwordx4 v[140:143], v[2:3]
	flat_load_dwordx4 v[136:139], v[2:3] offset:32
	flat_load_dwordx4 v[132:135], v[2:3] offset:64
	flat_load_dwordx4 v[128:131], v[2:3] offset:96
	v_mov_b32_e32 v17, v1
	v_add_u32_e32 v20, s61, v11
	v_lshrrev_b32_e32 v25, 1, v158
	v_bfe_u32 v26, v158, 1, 3
	v_lshl_add_u64 v[148:149], s[0:1], 0, v[16:17]
	v_lshlrev_b32_e32 v17, 3, v21
	v_add_u32_e32 v16, 8, v20
	v_ashrrev_i32_e32 v21, 31, v20
	v_or_b32_e32 v169, s16, v23
	v_or_b32_e32 v23, v17, v22
	v_lshlrev_b32_e32 v160, 2, v22
	v_bitop3_b32 v25, v25, v22, 7 bitop3:0x6c
	v_bitop3_b32 v28, v22, v26, 2 bitop3:0x36
	v_bitop3_b32 v29, v22, v26, 4 bitop3:0x36
	v_bitop3_b32 v26, v22, v26, 6 bitop3:0x36
	v_bitop3_b32 v22, v17, v18, v22 bitop3:0x36
	v_ashrrev_i32_e32 v17, 31, v16
	v_and_b32_e32 v27, 7, v12
	v_lshlrev_b64 v[20:21], 12, v[20:21]
	v_lshlrev_b64 v[16:17], 12, v[16:17]
	v_mov_b32_e32 v14, v1
	v_mov_b32_e32 v15, v1
	v_lshlrev_b32_e32 v170, 8, v24
	v_lshlrev_b32_e32 v168, 7, v24
	v_or_b32_e32 v165, v169, v24
	v_lshlrev_b32_e32 v174, 4, v22
	v_bitop3_b32 v22, v23, v18, 2 bitop3:0x36
	v_bitop3_b32 v24, v23, v18, 4 bitop3:0x36
	v_bitop3_b32 v18, v23, v18, 6 bitop3:0x36
	v_lshl_or_b32 v20, v19, 4, v20
	s_addk_i32 s16, 0x80
	v_lshl_or_b32 v16, v27, 4, v16
	v_lshl_add_u64 v[146:147], s[0:1], 0, v[0:1]
	v_add_u32_e32 v171, s17, v10
	v_mov_b32_e32 v0, v1
	v_mov_b32_e32 v2, v1
	v_mov_b32_e32 v3, v1
	v_mov_b32_e32 v4, v1
	v_mov_b32_e32 v6, v1
	v_mov_b32_e32 v7, v1
	v_mov_b32_e32 v8, v1
	v_mov_b32_e32 v9, v1
	v_mov_b32_e32 v10, v1
	v_mov_b32_e32 v11, v1
	v_mov_b32_e32 v12, v1
	v_mov_b32_e32 v13, v1
	v_lshlrev_b32_e32 v167, 4, v25
	v_lshlrev_b32_e32 v166, 4, v28
	v_lshlrev_b32_e32 v164, 4, v29
	v_lshlrev_b32_e32 v163, 4, v26
	v_lshlrev_b32_e32 v175, 4, v22
	v_lshlrev_b32_e32 v173, 4, v24
	v_lshlrev_b32_e32 v172, 4, v18
	v_lshl_add_u64 v[152:153], s[6:7], 0, v[20:21]
	s_lshr_b32 s61, s16, 6
	v_lshl_add_u64 v[154:155], s[6:7], 0, v[16:17]
	v_mov_b64_e32 v[30:31], v[14:15]
	v_mov_b64_e32 v[46:47], v[14:15]
	v_mov_b64_e32 v[62:63], v[14:15]
	v_mov_b64_e32 v[78:79], v[14:15]
	v_mov_b64_e32 v[94:95], v[14:15]
	v_or_b32_e32 v176, 31, v169
	s_add_i32 s62, s61, -2
	s_mov_b32 s63, 0
	s_mov_b32 s64, 0
	v_mov_b64_e32 v[28:29], v[12:13]
	v_mov_b64_e32 v[26:27], v[10:11]
	v_mov_b64_e32 v[24:25], v[8:9]
	v_mov_b64_e32 v[22:23], v[6:7]
	v_mov_b64_e32 v[20:21], v[4:5]
	v_mov_b64_e32 v[18:19], v[2:3]
	v_mov_b64_e32 v[16:17], v[0:1]
	v_mov_b64_e32 v[44:45], v[12:13]
	v_mov_b64_e32 v[42:43], v[10:11]
	v_mov_b64_e32 v[40:41], v[8:9]
	v_mov_b64_e32 v[38:39], v[6:7]
	v_mov_b64_e32 v[36:37], v[4:5]
	v_mov_b64_e32 v[34:35], v[2:3]
	v_mov_b64_e32 v[32:33], v[0:1]
	v_mov_b64_e32 v[60:61], v[12:13]
	v_mov_b64_e32 v[58:59], v[10:11]
	v_mov_b64_e32 v[56:57], v[8:9]
	v_mov_b64_e32 v[54:55], v[6:7]
	v_mov_b64_e32 v[52:53], v[4:5]
	v_mov_b64_e32 v[50:51], v[2:3]
	v_mov_b64_e32 v[48:49], v[0:1]
	v_mov_b64_e32 v[76:77], v[12:13]
	v_mov_b64_e32 v[74:75], v[10:11]
	v_mov_b64_e32 v[72:73], v[8:9]
	v_mov_b64_e32 v[70:71], v[6:7]
	v_mov_b64_e32 v[68:69], v[4:5]
	v_mov_b64_e32 v[66:67], v[2:3]
	v_mov_b64_e32 v[64:65], v[0:1]
	s_mov_b32 s65, 0
	v_mov_b64_e32 v[92:93], v[12:13]
	v_mov_b64_e32 v[90:91], v[10:11]
	v_mov_b64_e32 v[88:89], v[8:9]
	v_mov_b64_e32 v[86:87], v[6:7]
	v_mov_b64_e32 v[84:85], v[4:5]
	v_mov_b64_e32 v[82:83], v[2:3]
	v_mov_b64_e32 v[80:81], v[0:1]
	v_mov_b32_e32 v248, v1
	v_mov_b32_e32 v249, v1
	v_readfirstlane_b32 s100, v169
	s_waitcnt vmcnt(0) lgkmcnt(0)
	s_cmp_ge_u32 s65, s62
	s_mov_b64 s[4:5], -1
	s_cbranch_scc0 .LBB0_93
	s_branch .LBB0_92

; #define MFMA(a, b, c) __builtin_amdgcn_mfma_f32_32x32x16_bf16((a), (b), (c), 0, 0, 0)
; DI unsigned pack2(float a, float b) { fl2_t f = {a, b}; bf2_t r = __builtin_convertvector(f, bf2_t); return __builtin_bit_cast(unsigned, r); }
; DI int crow(int i, int h) { return (i & 3) + 8 * (i >> 2) + 4 * h; }
; template <int DK, int DV, int NM, bool CAUSAL> ...
;     ...
;     const bool skip = CAUSAL && (kt * 64 > q0w + 31);
;     if (!skip) {
;       const char* base = smem + (kt & 3) * STAGE;
;       f32x16 s[2];
; #pragma unroll
;       for (int sb = 0; sb < 2; ++sb) {
; #pragma unroll
;         for (int i = 0; i < 16; ++i) s[sb][i] = 0.f;
;         const char* pk = base + (sb * 32 + l31) * 256;
; #pragma unroll
;         for (int kc = 0; kc < NKC16; ++kc) {
;           const bf16x8 a = *(const bf16x8*)(pk + (((mymap * (DK / 8) + kc * 2 + h) ^ (l31 & 15)) * 16));
;           s[sb] = MFMA(a, qf[kc], s[sb]);
;         }
;         __builtin_amdgcn_sched_barrier(0);
;       }
;       const bool need_mask = CAUSAL && (kt * 64 + 63 > q0w);
;       const char* pv = base + KBYTES + l31 * 128;
;       const int vsw = (l31 >> 1) & 7;
;       bf16x8 pf[4];
;       auto expo = [&](int sb) {
; #pragma unroll
;         for (int i = 0; i < 16; ++i) {
;           float pz = __builtin_amdgcn_exp2f(s[sb][i]);
;           if (need_mask) {
;             const int key = kt * 64 + sb * 32 + crow(i, h);
;             if (key > q0w + l31) pz = 0.f;
;           }
;           s[sb][i] = pz;
;         }
; #pragma unroll
;         for (int k2 = 0; k2 < 2; ++k2) {
;           u4 pu;
;           pu.x = pack2(s[sb][k2 * 8 + 0], s[sb][k2 * 8 + 1]);
;           pu.y = pack2(s[sb][k2 * 8 + 2], s[sb][k2 * 8 + 3]);
;           pu.z = pack2(s[sb][k2 * 8 + 4], s[sb][k2 * 8 + 5]);
;           pu.w = pack2(s[sb][k2 * 8 + 6], s[sb][k2 * 8 + 7]);
;           pf[sb * 2 + k2] = __builtin_bit_cast(bf16x8, pu);
;         }
;       };
;       auto pvmm = [&](int ks) {
;         lacc = MFMA(ones, pf[ks], lacc);
; #pragma unroll
;         for (int d = 0; d < NDVB; ++d) {
;           const u4 au = *(const u4*)(pv + d * 32 * 128 + (((ks * 2 + h) ^ vsw) * 16));
;           o[d] = MFMA(__builtin_bit_cast(bf16x8, au), pf[ks], o[d]);
;         }
;       };
;       expo(0);
;       pvmm(0); pvmm(1);
;       expo(1);
;       pvmm(2); pvmm(3);
;       __builtin_amdgcn_sched_barrier(0);
.LBB0_97:
	s_add_i32 s4, s63, 63
	s_cmp_le_u32 s4, s100
	s_cbranch_scc0 .Lmy_dslow
	s_and_b32 s4, s64, 0x18000
	v_or_b32_e32 v0, s4, v170
	v_add_u32_e32 v6, v0, v174
	v_add_u32_e32 v7, v0, v175
	v_add_u32_e32 v8, v0, v173
	v_add_u32_e32 v9, v0, v172
	ds_read_b128 v[212:215], v6
	ds_read_b128 v[216:219], v7
	ds_read_b128 v[220:223], v8
	ds_read_b128 v[224:227], v9
	ds_read_b128 v[228:231], v6 offset:8192
	ds_read_b128 v[232:235], v7 offset:8192
	ds_read_b128 v[236:239], v8 offset:8192
	ds_read_b128 v[240:243], v9 offset:8192
	v_or_b32_e32 v0, s4, v168
	v_add_u32_e32 v10, v0, v167
	v_add_u32_e32 v11, v0, v166
	v_add_u32_e32 v12, v0, v164
	v_add_u32_e32 v13, v0, v163
	s_waitcnt lgkmcnt(7)
	v_mfma_f32_32x32x16_bf16 v[112:127], v[212:215], v[140:143], 0
	s_waitcnt lgkmcnt(6)
	v_mfma_f32_32x32x16_bf16 v[112:127], v[216:219], v[136:139], v[112:127]
	s_waitcnt lgkmcnt(5)
	v_mfma_f32_32x32x16_bf16 v[112:127], v[220:223], v[132:135], v[112:127]
	s_waitcnt lgkmcnt(4)
	v_mfma_f32_32x32x16_bf16 v[112:127], v[224:227], v[128:131], v[112:127]
	ds_read_b128 v[212:215], v10 offset:16384
	ds_read_b128 v[216:219], v10 offset:20480
	s_waitcnt lgkmcnt(5)
	v_mfma_f32_32x32x16_bf16 v[96:111], v[228:231], v[140:143], 0
	ds_read_b128 v[220:223], v10 offset:24576
	ds_read_b128 v[224:227], v10 offset:28672
	s_waitcnt lgkmcnt(6)
	v_mfma_f32_32x32x16_bf16 v[96:111], v[232:235], v[136:139], v[96:111]
	s_waitcnt lgkmcnt(5)
	v_mfma_f32_32x32x16_bf16 v[96:111], v[236:239], v[132:135], v[96:111]
	s_waitcnt lgkmcnt(4)
	v_mfma_f32_32x32x16_bf16 v[96:111], v[240:243], v[128:131], v[96:111]
	ds_read_b128 v[228:231], v11 offset:16384
	ds_read_b128 v[232:235], v11 offset:20480
	ds_read_b128 v[236:239], v11 offset:24576
	ds_read_b128 v[240:243], v11 offset:28672
	v_exp_f32_e32 v112, v112
	v_exp_f32_e32 v113, v113
	v_exp_f32_e32 v114, v114
	v_exp_f32_e32 v115, v115
	v_exp_f32_e32 v116, v116
	v_exp_f32_e32 v117, v117
	v_exp_f32_e32 v118, v118
	v_exp_f32_e32 v119, v119
	v_add_f32_e32 v248, v248, v112
	v_add_f32_e32 v249, v249, v113
	v_add_f32_e32 v248, v248, v114
	v_add_f32_e32 v249, v249, v115
	v_add_f32_e32 v248, v248, v116
	v_add_f32_e32 v249, v249, v117
	v_add_f32_e32 v248, v248, v118
	v_add_f32_e32 v249, v249, v119
	v_cvt_pk_bf16_f32 v186, v112, v113
	v_cvt_pk_bf16_f32 v187, v114, v115
	v_cvt_pk_bf16_f32 v188, v116, v117
	v_cvt_pk_bf16_f32 v189, v118, v119
	s_nop 0
	s_waitcnt lgkmcnt(7)
	v_mfma_f32_32x32x16_bf16 v[64:79], v[212:215], v[186:189], v[64:79]
	ds_read_b128 v[212:215], v12 offset:16384
	v_exp_f32_e32 v120, v120
	v_exp_f32_e32 v121, v121
	v_exp_f32_e32 v122, v122
	v_exp_f32_e32 v123, v123
	v_exp_f32_e32 v124, v124
	s_waitcnt lgkmcnt(7)
	v_mfma_f32_32x32x16_bf16 v[48:63], v[216:219], v[186:189], v[48:63]
	ds_read_b128 v[216:219], v12 offset:20480
	v_exp_f32_e32 v125, v125
	v_exp_f32_e32 v126, v126
	v_exp_f32_e32 v127, v127
	v_add_f32_e32 v248, v248, v120
	v_add_f32_e32 v249, v249, v121
	s_waitcnt lgkmcnt(7)
	v_mfma_f32_32x32x16_bf16 v[32:47], v[220:223], v[186:189], v[32:47]
	ds_read_b128 v[220:223], v12 offset:24576
	v_add_f32_e32 v248, v248, v122
	v_add_f32_e32 v249, v249, v123
	v_add_f32_e32 v248, v248, v124
	v_add_f32_e32 v249, v249, v125
	v_add_f32_e32 v248, v248, v126
	s_waitcnt lgkmcnt(7)
	v_mfma_f32_32x32x16_bf16 v[16:31], v[224:227], v[186:189], v[16:31]
	ds_read_b128 v[224:227], v12 offset:28672
	v_add_f32_e32 v249, v249, v127
	v_cvt_pk_bf16_f32 v190, v120, v121
	v_cvt_pk_bf16_f32 v191, v122, v123
	v_cvt_pk_bf16_f32 v192, v124, v125
	v_cvt_pk_bf16_f32 v193, v126, v127
	s_nop 0
	s_waitcnt lgkmcnt(7)
	v_mfma_f32_32x32x16_bf16 v[64:79], v[228:231], v[190:193], v[64:79]
	ds_read_b128 v[228:231], v13 offset:16384
	v_exp_f32_e32 v96, v96
	v_exp_f32_e32 v97, v97
	v_exp_f32_e32 v98, v98
	v_exp_f32_e32 v99, v99
	v_exp_f32_e32 v100, v100
	s_waitcnt lgkmcnt(7)
	v_mfma_f32_32x32x16_bf16 v[48:63], v[232:235], v[190:193], v[48:63]
	ds_read_b128 v[232:235], v13 offset:20480
	v_exp_f32_e32 v101, v101
	v_exp_f32_e32 v102, v102
	v_exp_f32_e32 v103, v103
	v_add_f32_e32 v248, v248, v96
	v_add_f32_e32 v249, v249, v97
	s_waitcnt lgkmcnt(7)
	v_mfma_f32_32x32x16_bf16 v[32:47], v[236:239], v[190:193], v[32:47]
	ds_read_b128 v[236:239], v13 offset:24576
	v_add_f32_e32 v248, v248, v98
	v_add_f32_e32 v249, v249, v99
	v_add_f32_e32 v248, v248, v100
	v_add_f32_e32 v249, v249, v101
	v_add_f32_e32 v248, v248, v102
	s_waitcnt lgkmcnt(7)
	v_mfma_f32_32x32x16_bf16 v[16:31], v[240:243], v[190:193], v[16:31]
	ds_read_b128 v[240:243], v13 offset:28672
	v_add_f32_e32 v249, v249, v103
	v_cvt_pk_bf16_f32 v244, v96, v97
	v_cvt_pk_bf16_f32 v245, v98, v99
	v_cvt_pk_bf16_f32 v246, v100, v101
	v_cvt_pk_bf16_f32 v247, v102, v103
	s_nop 0
	s_waitcnt lgkmcnt(7)
	v_mfma_f32_32x32x16_bf16 v[64:79], v[212:215], v[244:247], v[64:79]
	v_exp_f32_e32 v104, v104
	v_exp_f32_e32 v105, v105
	v_exp_f32_e32 v106, v106
	v_exp_f32_e32 v107, v107
	v_exp_f32_e32 v108, v108
	s_waitcnt lgkmcnt(6)
	v_mfma_f32_32x32x16_bf16 v[48:63], v[216:219], v[244:247], v[48:63]
	v_exp_f32_e32 v109, v109
	v_exp_f32_e32 v110, v110
	v_exp_f32_e32 v111, v111
	v_add_f32_e32 v248, v248, v104
	v_add_f32_e32 v249, v249, v105
	s_waitcnt lgkmcnt(5)
	v_mfma_f32_32x32x16_bf16 v[32:47], v[220:223], v[244:247], v[32:47]
	v_add_f32_e32 v248, v248, v106
	v_add_f32_e32 v249, v249, v107
	v_add_f32_e32 v248, v248, v108
	v_add_f32_e32 v249, v249, v109
	v_add_f32_e32 v248, v248, v110
	s_waitcnt lgkmcnt(4)
	v_mfma_f32_32x32x16_bf16 v[16:31], v[224:227], v[244:247], v[16:31]
	v_add_f32_e32 v249, v249, v111
	v_cvt_pk_bf16_f32 v2, v104, v105
	v_cvt_pk_bf16_f32 v3, v106, v107
	v_cvt_pk_bf16_f32 v4, v108, v109
	v_cvt_pk_bf16_f32 v5, v110, v111
	s_nop 0
	s_waitcnt lgkmcnt(3)
	v_mfma_f32_32x32x16_bf16 v[64:79], v[228:231], v[2:5], v[64:79]
	s_waitcnt lgkmcnt(2)
	v_mfma_f32_32x32x16_bf16 v[48:63], v[232:235], v[2:5], v[48:63]
	s_waitcnt lgkmcnt(1)
	v_mfma_f32_32x32x16_bf16 v[32:47], v[236:239], v[2:5], v[32:47]
	s_waitcnt lgkmcnt(0)
	v_mfma_f32_32x32x16_bf16 v[16:31], v[240:243], v[2:5], v[16:31]
	s_branch .LBB0_99

; template <int DK, int DV, int NM, bool CAUSAL> ...
;     ...
;   asm volatile("s_waitcnt lgkmcnt(0)" ::: "memory");
;   __builtin_amdgcn_s_barrier();
;   const float l_tot = lacc[0];
;   const float inv = 1.f / l_tot;
; #pragma unroll
;   for (int d = 0; d < NDVB; ++d)
; #pragma unroll
;     for (int i = 0; i < 16; ++i) o[d][i] *= inv;
;   float rn_out = 1.f;
;   if (NM == 2) {
;     float* buf = (float*)smem;
;     if (wave >= 4) {
; #pragma unroll
;       for (int d = 0; d < NDVB; ++d)
; #pragma unroll
;         for (int i = 0; i < 16; ++i) buf[(d * 16 + i) * 256 + (wave & 3) * 64 + lane] = o[d][i];
;     }
.LBB0_102:
	s_or_b64 exec, exec, s[16:17]
	v_add_f32_e32 v248, v248, v249
	s_nop 0
	v_mov_b32_e32 v249, v248
	s_nop 1
	v_permlane32_swap_b32 v249, v248
	v_add_f32_e32 v248, v248, v249
	v_add_f32_e32 v80, v80, v248
	v_div_scale_f32 v0, s[4:5], v80, v80, 1.0
	v_rcp_f32_e32 v2, v0
	s_waitcnt lgkmcnt(0)
	s_barrier
	v_fma_f32 v3, -v0, v2, 1.0
	v_fmac_f32_e32 v2, v3, v2
	v_div_scale_f32 v3, vcc, 1.0, v80, 1.0
	v_mul_f32_e32 v4, v3, v2
	v_fma_f32 v5, -v0, v4, v3
	v_fmac_f32_e32 v4, v5, v2
	v_fma_f32 v0, -v0, v4, v3
	v_div_fmas_f32 v0, v0, v2, v4
	v_div_fixup_f32 v0, v0, v80, 1.0
	v_pk_mul_f32 v[84:85], v[64:65], v[0:1] op_sel_hi:[1,0]
	v_pk_mul_f32 v[90:91], v[66:67], v[0:1] op_sel_hi:[1,0]
	v_pk_mul_f32 v[82:83], v[68:69], v[0:1] op_sel_hi:[1,0]
	v_pk_mul_f32 v[88:89], v[70:71], v[0:1] op_sel_hi:[1,0]
	v_pk_mul_f32 v[80:81], v[72:73], v[0:1] op_sel_hi:[1,0]
	v_pk_mul_f32 v[86:87], v[74:75], v[0:1] op_sel_hi:[1,0]
	v_pk_mul_f32 v[72:73], v[76:77], v[0:1] op_sel_hi:[1,0]
	v_pk_mul_f32 v[78:79], v[78:79], v[0:1] op_sel_hi:[1,0]
	v_pk_mul_f32 v[68:69], v[48:49], v[0:1] op_sel_hi:[1,0]
	v_pk_mul_f32 v[76:77], v[50:51], v[0:1] op_sel_hi:[1,0]
	v_pk_mul_f32 v[66:67], v[52:53], v[0:1] op_sel_hi:[1,0]
	v_pk_mul_f32 v[74:75], v[54:55], v[0:1] op_sel_hi:[1,0]
	v_pk_mul_f32 v[64:65], v[56:57], v[0:1] op_sel_hi:[1,0]
	v_pk_mul_f32 v[70:71], v[58:59], v[0:1] op_sel_hi:[1,0]
	v_pk_mul_f32 v[56:57], v[60:61], v[0:1] op_sel_hi:[1,0]
	v_pk_mul_f32 v[60:61], v[62:63], v[0:1] op_sel_hi:[1,0]
	v_pk_mul_f32 v[52:53], v[32:33], v[0:1] op_sel_hi:[1,0]
	v_pk_mul_f32 v[32:33], v[34:35], v[0:1] op_sel_hi:[1,0]
	v_pk_mul_f32 v[50:51], v[36:37], v[0:1] op_sel_hi:[1,0]
	v_pk_mul_f32 v[58:59], v[38:39], v[0:1] op_sel_hi:[1,0]
	v_pk_mul_f32 v[48:49], v[40:41], v[0:1] op_sel_hi:[1,0]
	v_pk_mul_f32 v[54:55], v[42:43], v[0:1] op_sel_hi:[1,0]
	v_pk_mul_f32 v[14:15], v[44:45], v[0:1] op_sel_hi:[1,0]
	v_pk_mul_f32 v[44:45], v[46:47], v[0:1] op_sel_hi:[1,0]
	v_pk_mul_f32 v[12:13], v[16:17], v[0:1] op_sel_hi:[1,0]
	v_pk_mul_f32 v[16:17], v[18:19], v[0:1] op_sel_hi:[1,0]
	v_pk_mul_f32 v[8:9], v[20:21], v[0:1] op_sel_hi:[1,0]
	v_pk_mul_f32 v[40:41], v[22:23], v[0:1] op_sel_hi:[1,0]
	v_pk_mul_f32 v[10:11], v[24:25], v[0:1] op_sel_hi:[1,0]
	v_pk_mul_f32 v[38:39], v[26:27], v[0:1] op_sel_hi:[1,0]
	v_pk_mul_f32 v[4:5], v[28:29], v[0:1] op_sel_hi:[1,0]
	v_pk_mul_f32 v[2:3], v[30:31], v[0:1] op_sel_hi:[1,0]
	v_cmp_lt_i32_e32 vcc, 3, v159
	s_and_saveexec_b64 s[4:5], vcc
	s_cbranch_execz .LBB0_104
	v_lshlrev_b32_e32 v0, 2, v161
	v_lshl_or_b32 v0, v162, 8, v0
	ds_write2st64_b32 v0, v84, v85 offset1:4
	ds_write2st64_b32 v0, v90, v91 offset0:8 offset1:12
	ds_write2st64_b32 v0, v82, v83 offset0:16 offset1:20
	ds_write2st64_b32 v0, v88, v89 offset0:24 offset1:28
	ds_write2st64_b32 v0, v80, v81 offset0:32 offset1:36
	ds_write2st64_b32 v0, v86, v87 offset0:40 offset1:44
	ds_write2st64_b32 v0, v72, v73 offset0:48 offset1:52
	ds_write2st64_b32 v0, v78, v79 offset0:56 offset1:60
	ds_write2st64_b32 v0, v68, v69 offset0:64 offset1:68
	ds_write2st64_b32 v0, v76, v77 offset0:72 offset1:76
	ds_write2st64_b32 v0, v66, v67 offset0:80 offset1:84
	ds_write2st64_b32 v0, v74, v75 offset0:88 offset1:92
	ds_write2st64_b32 v0, v64, v65 offset0:96 offset1:100
	ds_write2st64_b32 v0, v70, v71 offset0:104 offset1:108
	ds_write2st64_b32 v0, v56, v57 offset0:112 offset1:116
	ds_write2st64_b32 v0, v60, v61 offset0:120 offset1:124
	ds_write2st64_b32 v0, v52, v53 offset0:128 offset1:132
	ds_write2st64_b32 v0, v32, v33 offset0:136 offset1:140
	ds_write2st64_b32 v0, v50, v51 offset0:144 offset1:148
	ds_write2st64_b32 v0, v58, v59 offset0:152 offset1:156
	ds_write2st64_b32 v0, v48, v49 offset0:160 offset1:164
	ds_write2st64_b32 v0, v54, v55 offset0:168 offset1:172
	ds_write2st64_b32 v0, v14, v15 offset0:176 offset1:180
	ds_write2st64_b32 v0, v44, v45 offset0:184 offset1:188
	ds_write2st64_b32 v0, v12, v13 offset0:192 offset1:196
	ds_write2st64_b32 v0, v16, v17 offset0:200 offset1:204
	ds_write2st64_b32 v0, v8, v9 offset0:208 offset1:212
	ds_write2st64_b32 v0, v40, v41 offset0:216 offset1:220
	ds_write2st64_b32 v0, v10, v11 offset0:224 offset1:228
	ds_write2st64_b32 v0, v38, v39 offset0:232 offset1:236
	ds_write2st64_b32 v0, v4, v5 offset0:240 offset1:244
	ds_write2st64_b32 v0, v2, v3 offset0:248 offset1:252

; __global__ void __launch_bounds__(NTHR) mega_fwd(Params p) {
;   __shared__ __attribute__((aligned(16))) char smem[LDS_BYTES];
	.amdhsa_kernel _Z8mega_fwd6Params
		.amdhsa_group_segment_fixed_size 148480
		.amdhsa_private_segment_fixed_size 0
		.amdhsa_kernarg_size 504
		.amdhsa_user_sgpr_count 2
		.amdhsa_user_sgpr_dispatch_ptr 0
		.amdhsa_user_sgpr_queue_ptr 0
		.amdhsa_user_sgpr_kernarg_segment_ptr 1
		.amdhsa_user_sgpr_dispatch_id 0
		.amdhsa_user_sgpr_kernarg_preload_length 0
		.amdhsa_user_sgpr_kernarg_preload_offset 0
		.amdhsa_user_sgpr_private_segment_size 0
		.amdhsa_uses_dynamic_stack 0
		.amdhsa_enable_private_segment 0
		.amdhsa_system_sgpr_workgroup_id_x 1
		.amdhsa_system_sgpr_workgroup_id_y 0
		.amdhsa_system_sgpr_workgroup_id_z 0
		.amdhsa_system_sgpr_workgroup_info 0
		.amdhsa_system_vgpr_workitem_id 2
		.amdhsa_next_free_vgpr 254
		.amdhsa_next_free_sgpr 102
		.amdhsa_accum_offset 256
		.amdhsa_reserve_vcc 1
		.amdhsa_float_round_mode_32 0
		.amdhsa_float_round_mode_16_64 0
		.amdhsa_float_denorm_mode_32 3
		.amdhsa_float_denorm_mode_16_64 3
		.amdhsa_dx10_clamp 1
		.amdhsa_ieee_mode 1
		.amdhsa_fp16_overflow 0
		.amdhsa_tg_split 0
		.amdhsa_exception_fp_ieee_invalid_op 0
		.amdhsa_exception_fp_denorm_src 0
		.amdhsa_exception_fp_ieee_div_zero 0
		.amdhsa_exception_fp_ieee_overflow 0
		.amdhsa_exception_fp_ieee_underflow 0
		.amdhsa_exception_fp_ieee_inexact 0
		.amdhsa_exception_int_div_zero 0
	.end_amdhsa_kernel

; __global__ void __launch_bounds__(NTHR) mega_fwd(Params p) {
;   __shared__ __attribute__((aligned(16))) char smem[LDS_BYTES];
amdhsa.kernels:
  - .agpr_count:     0
    .args:
      - .offset:         0
        .size:           248
        .value_kind:     by_value
      - .offset:         248
        .size:           4
        .value_kind:     hidden_block_count_x
      - .offset:         252
        .size:           4
        .value_kind:     hidden_block_count_y
      - .offset:         256
        .size:           4
        .value_kind:     hidden_block_count_z
      - .offset:         260
        .size:           2
        .value_kind:     hidden_group_size_x
      - .offset:         262
        .size:           2
        .value_kind:     hidden_group_size_y
      - .offset:         264
        .size:           2
        .value_kind:     hidden_group_size_z
      - .offset:         266
        .size:           2
        .value_kind:     hidden_remainder_x
      - .offset:         268
        .size:           2
        .value_kind:     hidden_remainder_y
      - .offset:         270
        .size:           2
        .value_kind:     hidden_remainder_z
      - .offset:         288
        .size:           8
        .value_kind:     hidden_global_offset_x
      - .offset:         296
        .size:           8
        .value_kind:     hidden_global_offset_y
      - .offset:         304
        .size:           8
        .value_kind:     hidden_global_offset_z
      - .offset:         312
        .size:           2
        .value_kind:     hidden_grid_dims
      - .offset:         336
        .size:           8
        .value_kind:     hidden_multigrid_sync_arg
    .group_segment_fixed_size: 148480
    .kernarg_segment_align: 8
    .kernarg_segment_size: 504
    .language:       OpenCL C
    .language_version:
      - 2
      - 0
    .max_flat_workgroup_size: 512
    .name:           _Z8mega_fwd6Params
    .private_segment_fixed_size: 0
    .sgpr_count:     108
    .sgpr_spill_count: 249
    .symbol:         _Z8mega_fwd6Params.kd
    .uniform_work_group_size: 1
    .uses_dynamic_stack: false
    .vgpr_count:     254
    .vgpr_spill_count: 0
    .wavefront_size: 64
